# D1 seam split: XCD-local barrier + guarded overlay writes in the input projection epilogue
# speedup vs baseline: 1.0126x; 1.0126x over previous
; __device__ __forceinline__ unsigned xb_ld(unsigned* p)              { return __hip_atomic_load(p, __ATOMIC_RELAXED, __HIP_MEMORY_SCOPE_AGENT); }
; __device__ __forceinline__ unsigned xb_add(unsigned* p, unsigned v) { return __hip_atomic_fetch_add(p, v, __ATOMIC_RELAXED, __HIP_MEMORY_SCOPE_AGENT); }
; #define XB_SPIN(cond, bar) do { unsigned _sp = 0; while (cond) { __builtin_amdgcn_s_sleep(8); \
;     if ((++_sp & 255u) == 0u) { if (xb_ld(&(bar)[XB_TMO])) break; if (_sp > XB_SPIN_CAP) { atomicAdd(&(bar)[XB_TMO], 1u); break; } } } } while (0)
; __device__ __forceinline__ void xcd_barrier(const XcdBarrier& b) {
;     asm volatile("s_waitcnt vmcnt(0)" ::: "memory");
;     __syncthreads();
;     if (threadIdx.x == 0) {
;         unsigned* bar = b.bar;
;         __builtin_amdgcn_s_waitcnt(0);
;         unsigned nloc = b.st[0], nx = b.st[1];
;         if (nloc == 0u) { xcd_barrier_complete(bar, b.x, nloc, nx); b.st[0] = nloc; b.st[1] = nx; }
;         const unsigned old = xb_add(&bar[XB_XSUB(b.x)], 1u);
;         const unsigned gen = old / nloc;
;         if (old + 1u == (gen + 1u) * nloc) {
;             __builtin_amdgcn_fence(__ATOMIC_RELEASE, "agent");
;             asm volatile("s_waitcnt vmcnt(0)" ::: "memory");
;             const unsigned og = xb_add(&bar[XB_TOP], 1u);
;             const unsigned tg = og / nx;
;             if (og + 1u == (tg + 1u) * nx) xb_add(&bar[XB_TOPGEN], 1u);
;             else XB_SPIN(xb_ld(&bar[XB_TOPGEN]) == tg, bar);
;             __builtin_amdgcn_fence(__ATOMIC_ACQUIRE, "agent");
;             xb_add(&bar[XB_XGEN(b.x)], 1u);
;             asm volatile("s_waitcnt vmcnt(0)" ::: "memory");
;         } else {
;             XB_SPIN(xb_ld(&bar[XB_XGEN(b.x)]) == gen, bar);
;             __builtin_amdgcn_fence(__ATOMIC_ACQUIRE, "agent");
;             asm volatile("s_waitcnt vmcnt(0)" ::: "memory");
;         }
;     }
;     __syncthreads();
; }
.LBB0_502:
	v_mov_b32_e32 v14, 0x23084
	ds_read_b32 v14, v14
	v_readlane_b32 s4, v252, 23
	s_waitcnt lgkmcnt(0)
	v_readfirstlane_b32 s5, v14
	s_nop 3
	s_cmp_eq_u32 s5, 0
	s_cbranch_scc1 .Ld_full
	s_cmp_eq_u32 s4, 0
	s_cbranch_scc1 .Ld_first
	v_readlane_b32 s4, v252, 34
	v_readlane_b32 s5, v252, 35
	s_and_b32 s44, s2, 7
	s_lshl_b32 s44, s44, 3
	s_bfe_u32 s45, s2, 0x30003
	s_or_b32 s44, s44, s45
	s_lshl_b32 s44, s44, 5
	s_addk_i32 s44, 0x3600
	s_add_u32 s4, s4, s44
	s_addc_u32 s5, s5, 0
	v_mov_b32_e32 v14, 0x23088
	v_mov_b32_e32 v12, 4
	ds_add_rtn_u32 v13, v14, v12
	v_mov_b32_e32 v11, 1
	s_nop 1
	global_atomic_add v1, v11, s[4:5]
	s_waitcnt lgkmcnt(0)
	v_add_u32_e32 v13, 4, v13
	s_mov_b32 s46, 0

; __device__ __forceinline__ unsigned xb_ld(unsigned* p)              { return __hip_atomic_load(p, __ATOMIC_RELAXED, __HIP_MEMORY_SCOPE_AGENT); }
; __device__ __forceinline__ unsigned xb_add(unsigned* p, unsigned v) { return __hip_atomic_fetch_add(p, v, __ATOMIC_RELAXED, __HIP_MEMORY_SCOPE_AGENT); }
; #define XB_SPIN(cond, bar) do { unsigned _sp = 0; while (cond) { __builtin_amdgcn_s_sleep(8); \
;     if ((++_sp & 255u) == 0u) { if (xb_ld(&(bar)[XB_TMO])) break; if (_sp > XB_SPIN_CAP) { atomicAdd(&(bar)[XB_TMO], 1u); break; } } } } while (0)
; __device__ __forceinline__ void xcd_barrier(const XcdBarrier& b) {
;     asm volatile("s_waitcnt vmcnt(0)" ::: "memory");
;     __syncthreads();
;     if (threadIdx.x == 0) {
;         unsigned* bar = b.bar;
;         __builtin_amdgcn_s_waitcnt(0);
;         unsigned nloc = b.st[0], nx = b.st[1];
;         if (nloc == 0u) { xcd_barrier_complete(bar, b.x, nloc, nx); b.st[0] = nloc; b.st[1] = nx; }
;         const unsigned old = xb_add(&bar[XB_XSUB(b.x)], 1u);
;         const unsigned gen = old / nloc;
;         if (old + 1u == (gen + 1u) * nloc) {
;             __builtin_amdgcn_fence(__ATOMIC_RELEASE, "agent");
;             asm volatile("s_waitcnt vmcnt(0)" ::: "memory");
;             const unsigned og = xb_add(&bar[XB_TOP], 1u);
;             const unsigned tg = og / nx;
;             if (og + 1u == (tg + 1u) * nx) xb_add(&bar[XB_TOPGEN], 1u);
;             else XB_SPIN(xb_ld(&bar[XB_TOPGEN]) == tg, bar);
;             __builtin_amdgcn_fence(__ATOMIC_ACQUIRE, "agent");
;             xb_add(&bar[XB_XGEN(b.x)], 1u);
;             asm volatile("s_waitcnt vmcnt(0)" ::: "memory");
;         } else {
;             XB_SPIN(xb_ld(&bar[XB_XGEN(b.x)]) == gen, bar);
;             __builtin_amdgcn_fence(__ATOMIC_ACQUIRE, "agent");
;             asm volatile("s_waitcnt vmcnt(0)" ::: "memory");
;         }
;     }
;     __syncthreads();
; }
.Ld_first:
	v_readlane_b32 s4, v252, 34
	v_readlane_b32 s5, v252, 35
	v_mov_b32_e32 v11, 1
	v_mov_b32_e32 v14, 0x23090
	v_mov_b32_e32 v12, 0x100
	ds_add_u32 v14, v12
	s_nop 0
	global_atomic_add v1, v11, s[4:5] offset:-128
	v_readlane_b32 s4, v253, 44
	v_readlane_b32 s5, v253, 45
	v_mov_b32_e32 v14, 0x2308c
	ds_add_rtn_u32 v13, v14, v3
	s_nop 2
	global_atomic_add v1, v11, s[4:5] offset:128
	s_waitcnt lgkmcnt(0)
	v_add_u32_e32 v13, v13, v3
	s_mov_b32 s46, 0
.Ld1_lpoll:
	global_load_dword v12, v1, s[4:5] offset:128 sc1
	s_waitcnt vmcnt(0)
	v_cmp_ge_u32_e32 vcc, v12, v13
	s_cbranch_vccnz .Ld_ldone
	s_add_i32 s46, s46, 1
	s_cmp_lt_u32 s46, 0x2000
	s_cbranch_scc0 .Ld_ldone
	s_sleep 2
	s_branch .Ld1_lpoll

; __device__ __forceinline__ unsigned cvt_pk_bf16(float lo, float hi) { unsigned r; asm volatile("v_cvt_pk_bf16_f32 %0, %1, %2" : "=v"(r) : "v"(lo), "v"(hi)); return r; }
;     __device__ __forceinline__ void operator()(const f32x4 (&acc)[2][2][4][2], const Unit& u, int wr, int wc, int fr, int fq, int ui) const {
;     ...
;                     u32x4 w; w.x = cvt_pk_bf16(v0[0], v0[1]); w.y = cvt_pk_bf16(v0[2], v0[3]); w.z = cvt_pk_bf16(v1[0], v1[1]); w.w = cvt_pk_bf16(v1[2], v1[3]);
;                     const int cc = colt + bj * 128;
;                     if (sect == 2) *(u32x4*)(base + (size_t)r * DH + cc) = w;
;                     else *(u32x4*)(base + ((size_t)((r >> 13) * 8 + (cc >> 6)) * SEQ + (r & (SEQ - 1))) * 64 + (cc & 63)) = w;
.LBB0_608:
	v_mov_b32_e32 v18, 0x23090
	ds_read_b32 v18, v18
	v_mov_b32_e32 v19, 0x23094
	ds_read_b32 v19, v19
	s_waitcnt lgkmcnt(0)
	v_readfirstlane_b32 s4, v18
	v_readfirstlane_b32 s5, v19
	s_nop 3
	s_cmp_ge_u32 s5, s4
	s_cbranch_scc1 .Lqg_ok
	v_readlane_b32 s22, v252, 34
	v_readlane_b32 s23, v252, 35
	v_mov_b32_e32 v18, 0
	s_mov_b32 s50, 0
.Lqg_poll:
	s_nop 3
	global_load_dword v19, v18, s[22:23] offset:-128 sc1
	s_waitcnt vmcnt(0)
	v_readfirstlane_b32 s5, v19
	s_nop 3
	s_cmp_ge_u32 s5, s4
	s_cbranch_scc1 .Lqg_conf
	s_add_i32 s50, s50, 1
	s_cmp_lt_u32 s50, 0x2000
	s_cbranch_scc0 .Lqg_conf
	s_sleep 2
	s_branch .Lqg_poll
.Lqg_conf:
	v_mov_b32_e32 v18, 0x23094
	v_mov_b32_e32 v19, s4
	ds_write_b32 v18, v19
